# q-projection rope epilogue: cos/sin loads of odd row groups issued with the preceding even group (spare registers, counted waits)
# baseline (speedup 1.0000x reference)
; #define PG8_STAGE(bufoff, gbase, voff) do { _Pragma("unroll") for (int _i = 0; _i < 2; ++_i) \
;         __builtin_amdgcn_global_load_lds((const unsigned*)((const char*)(gbase) + (voff)[_i]), (PG8_LAS unsigned*)(lds + (bufoff) + ldsw + _i * 8192), 16, 0, 0); } while (0)
; #define PG8_LDA(dst, b, h) do { _Pragma("unroll") for (int m = 0; m < 4; ++m) _Pragma("unroll") for (int k = 0; k < 2; ++k) dst[m][k] = *(const PG8_LAS bf16x8*)(lds + PG8_SA(b, h) + aoff + m * 2048 + k * 1024); } while (0)
; #define PG8_LDB(dst, b, h) do { _Pragma("unroll") for (int n = 0; n < 2; ++n) _Pragma("unroll") for (int k = 0; k < 2; ++k) dst[n][k] = *(const PG8_LAS bf16x8*)(lds + PG8_SB(b, h) + boff + n * 2048 + k * 1024); } while (0)
; #define PG8_MMA(ai, bj, At, Bt) do { __builtin_amdgcn_s_setprio(1); _Pragma("unroll") for (int m = 0; m < 4; ++m) _Pragma("unroll") for (int n = 0; n < 2; ++n) _Pragma("unroll") for (int k = 0; k < 2; ++k) \
;         acc[ai][bj][m][n] = __builtin_amdgcn_mfma_f32_16x16x32_bf16(Bt[n][k], At[m][k], acc[ai][bj][m][n], 0, 0, 0); __builtin_amdgcn_s_setprio(0); } while (0)
; #define PG8_WAIT_L(n) asm volatile("s_waitcnt lgkmcnt(" #n ")" ::: "memory")
; #define PG8_BAR __builtin_amdgcn_s_barrier()
; #define PG8_SCHED __builtin_amdgcn_sched_barrier(0)
; template <class Epi, class Sched, bool ALIGN_EPI = false, bool SP2 = false>
; __device__ __forceinline__ void gemm_phase(PG8_LAS unsigned char* lds, const Gemm g, const Sched& S, const Epi& E) {
;     ...
;             PG8_LDB(B0, 0, 0); PG8_SCHED; PG8_LDA(At, 0, 0); PG8_STAGE(PG8_SA(1, 1), a1 + hstepA, voffA);
;             PG8_WAIT_L(8); PG8_BAR; PG8_WAIT_L(0); PG8_MMA(0, 0, At, B0); PG8_BAR; PG8_SCHED;
;             PG8_LDB(B1, 0, 1); PG8_STAGE(PG8_SB(0, 0), b2, voffB);
;             PG8_BAR; PG8_WAIT_L(0); PG8_MMA(0, 1, At, B1); PG8_BAR;
;             PG8_LDA(At, 0, 1); PG8_STAGE(PG8_SA(0, 0), a2, voffA);
;             PG8_BAR; PG8_WAIT_L(0); PG8_MMA(1, 0, At, B0); PG8_BAR; PG8_SCHED;
.LBB0_364:
	ds_read_b128 v[146:149], v155
	ds_read_b128 v[158:161], v155 offset:1024
	ds_read_b128 v[162:165], v155 offset:2048
	ds_read_b128 v[170:173], v155 offset:3072
	s_add_u32 s44, s26, 0xfffe0080
	s_addc_u32 s45, s27, -1
	s_cmp_eq_u32 s80, 4
	s_cselect_b32 s51, s23, s45
	s_cselect_b32 s50, s52, s44
	s_cselect_b32 s45, s37, s79
	s_cselect_b32 s44, s53, s69
	v_lshl_add_u64 v[150:151], s[26:27], 0, v[138:139]
	s_add_i32 m0, s65, 0xc000
	ds_read_b128 v[174:177], v156
	ds_read_b128 v[178:181], v156 offset:1024
	ds_read_b128 v[182:185], v156 offset:2048
	ds_read_b128 v[186:189], v156 offset:3072
	ds_read_b128 v[190:193], v156 offset:4096
	ds_read_b128 v[194:197], v156 offset:5120
	ds_read_b128 v[198:201], v156 offset:6144
	ds_read_b128 v[202:205], v156 offset:7168
	global_load_lds_dwordx4 v[150:151], off
	v_lshl_add_u64 v[150:151], s[26:27], 0, v[140:141]
	s_add_i32 m0, s65, 0xe000
	s_nop 0
	global_load_lds_dwordx4 v[150:151], off
	s_waitcnt lgkmcnt(8)
	s_barrier
	s_waitcnt lgkmcnt(0)
	s_setprio 1
	s_waitcnt lgkmcnt(0)
	v_mfma_f32_16x16x32_bf16 v[124:127], v[146:149], v[174:177], v[124:127]
	v_mfma_f32_16x16x32_bf16 v[120:123], v[162:165], v[174:177], v[120:123]
	v_mfma_f32_16x16x32_bf16 v[108:111], v[146:149], v[182:185], v[108:111]
	v_mfma_f32_16x16x32_bf16 v[104:107], v[162:165], v[182:185], v[104:107]
	v_mfma_f32_16x16x32_bf16 v[92:95], v[146:149], v[190:193], v[92:95]
	v_mfma_f32_16x16x32_bf16 v[88:91], v[162:165], v[190:193], v[88:91]
	v_mfma_f32_16x16x32_bf16 v[76:79], v[146:149], v[198:201], v[76:79]
	v_mfma_f32_16x16x32_bf16 v[72:75], v[162:165], v[198:201], v[72:75]
	v_mfma_f32_16x16x32_bf16 v[124:127], v[158:161], v[178:181], v[124:127]
	v_mfma_f32_16x16x32_bf16 v[120:123], v[170:173], v[178:181], v[120:123]
	v_mfma_f32_16x16x32_bf16 v[108:111], v[158:161], v[186:189], v[108:111]
	v_mfma_f32_16x16x32_bf16 v[104:107], v[170:173], v[186:189], v[104:107]
	v_mfma_f32_16x16x32_bf16 v[92:95], v[158:161], v[194:197], v[92:95]
	v_mfma_f32_16x16x32_bf16 v[88:91], v[170:173], v[194:197], v[88:91]
	v_mfma_f32_16x16x32_bf16 v[76:79], v[158:161], v[202:205], v[76:79]
	v_mfma_f32_16x16x32_bf16 v[72:75], v[170:173], v[202:205], v[72:75]
	s_setprio 0
	s_barrier
	s_add_i32 s81, s55, s63
	v_lshl_add_u64 v[150:151], s[44:45], 0, v[130:131]
	s_mov_b32 m0, s81
	ds_read_b128 v[210:213], v157
	ds_read_b128 v[214:217], v157 offset:1024
	ds_read_b128 v[218:221], v157 offset:2048
	ds_read_b128 v[222:225], v157 offset:3072
	global_load_lds_dwordx4 v[150:151], off
	v_lshl_add_u64 v[166:167], s[44:45], 0, v[134:135]
	s_add_i32 m0, s81, 0x2000
	s_nop 0
	global_load_lds_dwordx4 v[166:167], off
	s_barrier
	s_waitcnt lgkmcnt(0)
	s_setprio 1
	s_waitcnt lgkmcnt(0)
	v_mfma_f32_16x16x32_bf16 v[116:119], v[210:213], v[174:177], v[116:119]
	v_mfma_f32_16x16x32_bf16 v[112:115], v[218:221], v[174:177], v[112:115]
	v_mfma_f32_16x16x32_bf16 v[100:103], v[210:213], v[182:185], v[100:103]
	v_mfma_f32_16x16x32_bf16 v[96:99], v[218:221], v[182:185], v[96:99]
	v_mfma_f32_16x16x32_bf16 v[84:87], v[210:213], v[190:193], v[84:87]
	v_mfma_f32_16x16x32_bf16 v[80:83], v[218:221], v[190:193], v[80:83]
	v_mfma_f32_16x16x32_bf16 v[68:71], v[210:213], v[198:201], v[68:71]
	v_mfma_f32_16x16x32_bf16 v[64:67], v[218:221], v[198:201], v[64:67]
	v_mfma_f32_16x16x32_bf16 v[116:119], v[214:217], v[178:181], v[116:119]
	v_mfma_f32_16x16x32_bf16 v[112:115], v[222:225], v[178:181], v[112:115]
	v_mfma_f32_16x16x32_bf16 v[100:103], v[214:217], v[186:189], v[100:103]
	v_mfma_f32_16x16x32_bf16 v[96:99], v[222:225], v[186:189], v[96:99]
	v_mfma_f32_16x16x32_bf16 v[84:87], v[214:217], v[194:197], v[84:87]
	v_mfma_f32_16x16x32_bf16 v[80:83], v[222:225], v[194:197], v[80:83]
	v_mfma_f32_16x16x32_bf16 v[68:71], v[214:217], v[202:205], v[68:71]
	v_mfma_f32_16x16x32_bf16 v[64:67], v[222:225], v[202:205], v[64:67]
	s_setprio 0
	s_mov_b32 m0, s65
	v_lshl_add_u64 v[206:207], s[50:51], 0, v[128:129]
	s_barrier
	ds_read_b128 v[174:177], v156 offset:16384
	ds_read_b128 v[178:181], v156 offset:17408
	ds_read_b128 v[182:185], v156 offset:18432
	ds_read_b128 v[186:189], v156 offset:19456
	ds_read_b128 v[190:193], v156 offset:20480
	ds_read_b128 v[194:197], v156 offset:21504
	ds_read_b128 v[198:201], v156 offset:22528
	ds_read_b128 v[202:205], v156 offset:23552
	global_load_lds_dwordx4 v[206:207], off
	v_lshl_add_u64 v[226:227], s[50:51], 0, v[132:133]
	s_mov_b32 m0, s66
	s_nop 0
	global_load_lds_dwordx4 v[226:227], off
	s_barrier
	s_waitcnt lgkmcnt(0)
	s_setprio 1
	s_waitcnt lgkmcnt(0)
	v_mfma_f32_16x16x32_bf16 v[60:63], v[146:149], v[174:177], v[60:63]
	v_mfma_f32_16x16x32_bf16 v[56:59], v[162:165], v[174:177], v[56:59]
	v_mfma_f32_16x16x32_bf16 v[44:47], v[146:149], v[182:185], v[44:47]
	v_mfma_f32_16x16x32_bf16 v[40:43], v[162:165], v[182:185], v[40:43]
	v_mfma_f32_16x16x32_bf16 v[28:31], v[146:149], v[190:193], v[28:31]
	v_mfma_f32_16x16x32_bf16 v[24:27], v[162:165], v[190:193], v[24:27]
	v_mfma_f32_16x16x32_bf16 v[12:15], v[146:149], v[198:201], v[12:15]
	v_mfma_f32_16x16x32_bf16 v[8:11], v[162:165], v[198:201], v[8:11]
	v_mfma_f32_16x16x32_bf16 v[60:63], v[158:161], v[178:181], v[60:63]
	v_mfma_f32_16x16x32_bf16 v[56:59], v[170:173], v[178:181], v[56:59]
	v_mfma_f32_16x16x32_bf16 v[44:47], v[158:161], v[186:189], v[44:47]
	v_mfma_f32_16x16x32_bf16 v[40:43], v[170:173], v[186:189], v[40:43]
	v_mfma_f32_16x16x32_bf16 v[28:31], v[158:161], v[194:197], v[28:31]
	v_mfma_f32_16x16x32_bf16 v[24:27], v[170:173], v[194:197], v[24:27]
	v_mfma_f32_16x16x32_bf16 v[12:15], v[158:161], v[202:205], v[12:15]
	v_mfma_f32_16x16x32_bf16 v[8:11], v[170:173], v[202:205], v[8:11]
	s_setprio 0
	s_barrier
; #define PG8_STAGE(bufoff, gbase, voff) do { _Pragma("unroll") for (int _i = 0; _i < 2; ++_i) \
;         __builtin_amdgcn_global_load_lds((const unsigned*)((const char*)(gbase) + (voff)[_i]), (PG8_LAS unsigned*)(lds + (bufoff) + ldsw + _i * 8192), 16, 0, 0); } while (0)
; #define PG8_LDA(dst, b, h) do { _Pragma("unroll") for (int m = 0; m < 4; ++m) _Pragma("unroll") for (int k = 0; k < 2; ++k) dst[m][k] = *(const PG8_LAS bf16x8*)(lds + PG8_SA(b, h) + aoff + m * 2048 + k * 1024); } while (0)
; #define PG8_LDB(dst, b, h) do { _Pragma("unroll") for (int n = 0; n < 2; ++n) _Pragma("unroll") for (int k = 0; k < 2; ++k) dst[n][k] = *(const PG8_LAS bf16x8*)(lds + PG8_SB(b, h) + boff + n * 2048 + k * 1024); } while (0)
; #define PG8_MMA(ai, bj, At, Bt) do { __builtin_amdgcn_s_setprio(1); _Pragma("unroll") for (int m = 0; m < 4; ++m) _Pragma("unroll") for (int n = 0; n < 2; ++n) _Pragma("unroll") for (int k = 0; k < 2; ++k) \
;         acc[ai][bj][m][n] = __builtin_amdgcn_mfma_f32_16x16x32_bf16(Bt[n][k], At[m][k], acc[ai][bj][m][n], 0, 0, 0); __builtin_amdgcn_s_setprio(0); } while (0)
; #define PG8_WAIT_V(n) asm volatile("s_waitcnt vmcnt(" #n ")" ::: "memory")
; #define PG8_WAIT_L(n) asm volatile("s_waitcnt lgkmcnt(" #n ")" ::: "memory")
; #define PG8_BAR __builtin_amdgcn_s_barrier()
; #define PG8_SCHED __builtin_amdgcn_sched_barrier(0)
; template <class Epi, class Sched, bool ALIGN_EPI = false, bool SP2 = false>
; __device__ __forceinline__ void gemm_phase(PG8_LAS unsigned char* lds, const Gemm g, const Sched& S, const Epi& E) {
;     ...
;             PG8_STAGE(PG8_SB(0, 1), b2 + hstepB, voffB);
;             PG8_WAIT_V(6); PG8_BAR; PG8_MMA(1, 1, At, B1); PG8_BAR;
;             PG8_LDB(B0, 1, 0); PG8_SCHED; PG8_LDA(At, 1, 0); PG8_STAGE(PG8_SA(0, 1), a2 + hstepA, voffA);
;             PG8_WAIT_L(8); PG8_BAR; PG8_WAIT_L(0); PG8_MMA(0, 0, At, B0); PG8_BAR; PG8_SCHED;
;             PG8_LDB(B1, 1, 1); PG8_STAGE(PG8_SB(1, 0), b3, voffB);
;             PG8_BAR; PG8_WAIT_L(0); PG8_MMA(0, 1, At, B1); PG8_BAR;
;             PG8_LDA(At, 1, 1); PG8_STAGE(PG8_SA(1, 0), a3, voffA);
;             PG8_BAR; PG8_WAIT_L(0); PG8_MMA(1, 0, At, B0); PG8_BAR; PG8_SCHED;
	s_add_u32 s82, s44, 0x20000
	s_addc_u32 s83, s45, 0
	s_add_i32 s81, s77, s63
	v_lshl_add_u64 v[146:147], s[82:83], 0, v[130:131]
	s_mov_b32 m0, s81
	s_nop 0
	global_load_lds_dwordx4 v[146:147], off
	v_lshl_add_u64 v[146:147], s[82:83], 0, v[134:135]
	s_add_i32 m0, s81, 0x2000
	s_nop 0
	global_load_lds_dwordx4 v[146:147], off
	s_waitcnt vmcnt(6)
	s_barrier
	s_setprio 1
	v_mfma_f32_16x16x32_bf16 v[52:55], v[210:213], v[174:177], v[52:55]
	v_mfma_f32_16x16x32_bf16 v[48:51], v[218:221], v[174:177], v[48:51]
	v_mfma_f32_16x16x32_bf16 v[36:39], v[210:213], v[182:185], v[36:39]
	v_mfma_f32_16x16x32_bf16 v[32:35], v[218:221], v[182:185], v[32:35]
	v_mfma_f32_16x16x32_bf16 v[20:23], v[210:213], v[190:193], v[20:23]
	v_mfma_f32_16x16x32_bf16 v[16:19], v[218:221], v[190:193], v[16:19]
	v_mfma_f32_16x16x32_bf16 v[4:7], v[210:213], v[198:201], v[4:7]
	v_mfma_f32_16x16x32_bf16 v[0:3], v[218:221], v[198:201], v[0:3]
	v_mfma_f32_16x16x32_bf16 v[52:55], v[214:217], v[178:181], v[52:55]
	v_mfma_f32_16x16x32_bf16 v[48:51], v[222:225], v[178:181], v[48:51]
	v_mfma_f32_16x16x32_bf16 v[36:39], v[214:217], v[186:189], v[36:39]
	v_mfma_f32_16x16x32_bf16 v[32:35], v[222:225], v[186:189], v[32:35]
	v_mfma_f32_16x16x32_bf16 v[20:23], v[214:217], v[194:197], v[20:23]
	v_mfma_f32_16x16x32_bf16 v[16:19], v[222:225], v[194:197], v[16:19]
	v_mfma_f32_16x16x32_bf16 v[4:7], v[214:217], v[202:205], v[4:7]
	v_mfma_f32_16x16x32_bf16 v[0:3], v[222:225], v[202:205], v[0:3]
	s_setprio 0
	s_add_i32 s81, 0, 0x18000
	v_add_u32_e32 v169, s81, v153
	s_barrier
	ds_read_b128 v[146:149], v169
	ds_read_b128 v[158:161], v169 offset:1024
	ds_read_b128 v[162:165], v169 offset:2048
	ds_read_b128 v[170:173], v169 offset:3072
	s_add_u32 s50, s50, 0x20000
	s_addc_u32 s51, s51, 0
	s_mov_b32 m0, s67
	v_lshl_add_u64 v[210:211], s[50:51], 0, v[128:129]
	ds_read_b128 v[174:177], v156 offset:32768
	ds_read_b128 v[178:181], v156 offset:33792
	ds_read_b128 v[182:185], v156 offset:34816
	ds_read_b128 v[186:189], v156 offset:35840
	ds_read_b128 v[190:193], v156 offset:36864
	ds_read_b128 v[194:197], v156 offset:37888
	ds_read_b128 v[198:201], v156 offset:38912
	ds_read_b128 v[202:205], v156 offset:39936
	global_load_lds_dwordx4 v[210:211], off
	v_lshl_add_u64 v[210:211], s[50:51], 0, v[132:133]
	s_mov_b32 m0, s74
	s_nop 0
	global_load_lds_dwordx4 v[210:211], off
	s_waitcnt lgkmcnt(8)
	s_barrier
	s_waitcnt lgkmcnt(0)
	s_setprio 1
	s_waitcnt lgkmcnt(0)
	v_mfma_f32_16x16x32_bf16 v[124:127], v[146:149], v[174:177], v[124:127]
	v_mfma_f32_16x16x32_bf16 v[120:123], v[162:165], v[174:177], v[120:123]
	v_mfma_f32_16x16x32_bf16 v[108:111], v[146:149], v[182:185], v[108:111]
	v_mfma_f32_16x16x32_bf16 v[104:107], v[162:165], v[182:185], v[104:107]
	v_mfma_f32_16x16x32_bf16 v[92:95], v[146:149], v[190:193], v[92:95]
	v_mfma_f32_16x16x32_bf16 v[88:91], v[162:165], v[190:193], v[88:91]
	v_mfma_f32_16x16x32_bf16 v[76:79], v[146:149], v[198:201], v[76:79]
	v_mfma_f32_16x16x32_bf16 v[72:75], v[162:165], v[198:201], v[72:75]
	v_mfma_f32_16x16x32_bf16 v[124:127], v[158:161], v[178:181], v[124:127]
	v_mfma_f32_16x16x32_bf16 v[120:123], v[170:173], v[178:181], v[120:123]
	v_mfma_f32_16x16x32_bf16 v[108:111], v[158:161], v[186:189], v[108:111]
	v_mfma_f32_16x16x32_bf16 v[104:107], v[170:173], v[186:189], v[104:107]
	v_mfma_f32_16x16x32_bf16 v[92:95], v[158:161], v[194:197], v[92:95]
	v_mfma_f32_16x16x32_bf16 v[88:91], v[170:173], v[194:197], v[88:91]
	v_mfma_f32_16x16x32_bf16 v[76:79], v[158:161], v[202:205], v[76:79]
	v_mfma_f32_16x16x32_bf16 v[72:75], v[170:173], v[202:205], v[72:75]
	s_setprio 0
	s_barrier
	s_add_i32 s50, 0, 0x1c000
	s_add_i32 s51, s81, s63
	v_add_u32_e32 v169, s50, v153
	v_lshl_add_u64 v[150:151], v[150:151], 0, s[0:1]
	s_mov_b32 m0, s51
	ds_read_b128 v[210:213], v169
	ds_read_b128 v[214:217], v169 offset:1024
	ds_read_b128 v[218:221], v169 offset:2048
	ds_read_b128 v[222:225], v169 offset:3072
	global_load_lds_dwordx4 v[150:151], off
	v_lshl_add_u64 v[150:151], v[166:167], 0, s[0:1]
	s_add_i32 m0, s51, 0x2000
	s_nop 0
	global_load_lds_dwordx4 v[150:151], off
	s_barrier
	s_waitcnt lgkmcnt(0)
	s_setprio 1
	s_waitcnt lgkmcnt(0)
	v_mfma_f32_16x16x32_bf16 v[116:119], v[210:213], v[174:177], v[116:119]
	v_mfma_f32_16x16x32_bf16 v[112:115], v[218:221], v[174:177], v[112:115]
	v_mfma_f32_16x16x32_bf16 v[100:103], v[210:213], v[182:185], v[100:103]
	v_mfma_f32_16x16x32_bf16 v[96:99], v[218:221], v[182:185], v[96:99]
	v_mfma_f32_16x16x32_bf16 v[84:87], v[210:213], v[190:193], v[84:87]
	v_mfma_f32_16x16x32_bf16 v[80:83], v[218:221], v[190:193], v[80:83]
	v_mfma_f32_16x16x32_bf16 v[68:71], v[210:213], v[198:201], v[68:71]
	v_mfma_f32_16x16x32_bf16 v[64:67], v[218:221], v[198:201], v[64:67]
	v_mfma_f32_16x16x32_bf16 v[116:119], v[214:217], v[178:181], v[116:119]
	v_mfma_f32_16x16x32_bf16 v[112:115], v[222:225], v[178:181], v[112:115]
	v_mfma_f32_16x16x32_bf16 v[100:103], v[214:217], v[186:189], v[100:103]
	v_mfma_f32_16x16x32_bf16 v[96:99], v[222:225], v[186:189], v[96:99]
	v_mfma_f32_16x16x32_bf16 v[84:87], v[214:217], v[194:197], v[84:87]
	v_mfma_f32_16x16x32_bf16 v[80:83], v[222:225], v[194:197], v[80:83]
	v_mfma_f32_16x16x32_bf16 v[68:71], v[214:217], v[202:205], v[68:71]
	v_mfma_f32_16x16x32_bf16 v[64:67], v[222:225], v[202:205], v[64:67]
	s_setprio 0
	s_mov_b32 m0, s93
	v_lshl_add_u64 v[150:151], v[206:207], 0, s[0:1]
	s_barrier
	ds_read_b128 v[174:177], v156 offset:49152
	ds_read_b128 v[178:181], v156 offset:50176
	ds_read_b128 v[182:185], v156 offset:51200
	ds_read_b128 v[186:189], v156 offset:52224
	ds_read_b128 v[190:193], v156 offset:53248
	ds_read_b128 v[194:197], v156 offset:54272
	ds_read_b128 v[198:201], v156 offset:55296
	ds_read_b128 v[202:205], v156 offset:56320
	global_load_lds_dwordx4 v[150:151], off
	v_lshl_add_u64 v[150:151], v[226:227], 0, s[0:1]
	s_mov_b32 m0, s3
	s_nop 0
	global_load_lds_dwordx4 v[150:151], off
	s_barrier
; #define PG8_STAGE(bufoff, gbase, voff) do { _Pragma("unroll") for (int _i = 0; _i < 2; ++_i) \
;         __builtin_amdgcn_global_load_lds((const unsigned*)((const char*)(gbase) + (voff)[_i]), (PG8_LAS unsigned*)(lds + (bufoff) + ldsw + _i * 8192), 16, 0, 0); } while (0)
; #define PG8_WAIT_V(n) asm volatile("s_waitcnt vmcnt(" #n ")" ::: "memory")
; #define PG8_WAIT_L(n) asm volatile("s_waitcnt lgkmcnt(" #n ")" ::: "memory")
; template <class Epi, class Sched, bool ALIGN_EPI = false, bool SP2 = false>
; __device__ __forceinline__ void gemm_phase(PG8_LAS unsigned char* lds, const Gemm g, const Sched& S, const Epi& E) {
;     ...
;             PG8_BAR; PG8_WAIT_L(0); PG8_MMA(1, 0, At, B0); PG8_BAR; PG8_SCHED;
;             PG8_STAGE(PG8_SB(1, 1), b3 + hstepB, voffB);
;             PG8_WAIT_V(6); PG8_BAR; PG8_MMA(1, 1, At, B1); PG8_BAR;
;     __device__ __forceinline__ void operator()(const f32x4 (&acc)[2][2][4][2], const Unit& u, int wr, int wc, int fr, int fq) const {
;     ...
;         const bool rope = u.pn >= rope_pn0;
; #pragma unroll
;         for (int ai = 0; ai < 2; ++ai)
; #pragma unroll
;             for (int m = 0; m < 4; ++m) { const int row = row0 + ai * HALF + m * 16; const float s = mult;
;                 f32x4 a0 = acc[ai][0][m][0] * s, a1 = acc[ai][0][m][1] * s, b0 = acc[ai][1][m][0] * s, b1 = acc[ai][1][m][1] * s;
;                 if (rope) { const f32x4* cp = (const f32x4*)(cs + (size_t)row * 64 + 16 * fq);
;                     const f32x4 c0 = cp[0], c1 = cp[1], c2 = cp[2], c3 = cp[3];
;                     f32x4 x0, x1, y0, y1;
;                     x0[0] = a0[0] * c0[0] - b0[0] * c0[1]; y0[0] = b0[0] * c0[0] + a0[0] * c0[1];
;                     x0[1] = a0[1] * c0[2] - b0[1] * c0[3]; y0[1] = b0[1] * c0[2] + a0[1] * c0[3];
;                     x0[2] = a0[2] * c1[0] - b0[2] * c1[1]; y0[2] = b0[2] * c1[0] + a0[2] * c1[1];
;                     x0[3] = a0[3] * c1[2] - b0[3] * c1[3]; y0[3] = b0[3] * c1[2] + a0[3] * c1[3];
;                     x1[0] = a1[0] * c2[0] - b1[0] * c2[1]; y1[0] = b1[0] * c2[0] + a1[0] * c2[1];
;                     x1[1] = a1[1] * c2[2] - b1[1] * c2[3]; y1[1] = b1[1] * c2[2] + a1[1] * c2[3];
;                     x1[2] = a1[2] * c3[0] - b1[2] * c3[1]; y1[2] = b1[2] * c3[0] + a1[2] * c3[1];
;                     x1[3] = a1[3] * c3[2] - b1[3] * c3[3]; y1[3] = b1[3] * c3[2] + a1[3] * c3[3];
	s_waitcnt lgkmcnt(0)
	s_setprio 1
	s_waitcnt lgkmcnt(0)
	v_mfma_f32_16x16x32_bf16 v[60:63], v[146:149], v[174:177], v[60:63]
	v_mfma_f32_16x16x32_bf16 v[56:59], v[162:165], v[174:177], v[56:59]
	v_mfma_f32_16x16x32_bf16 v[44:47], v[146:149], v[182:185], v[44:47]
	v_mfma_f32_16x16x32_bf16 v[40:43], v[162:165], v[182:185], v[40:43]
	v_mfma_f32_16x16x32_bf16 v[28:31], v[146:149], v[190:193], v[28:31]
	v_mfma_f32_16x16x32_bf16 v[24:27], v[162:165], v[190:193], v[24:27]
	v_mfma_f32_16x16x32_bf16 v[12:15], v[146:149], v[198:201], v[12:15]
	v_mfma_f32_16x16x32_bf16 v[8:11], v[162:165], v[198:201], v[8:11]
	v_mfma_f32_16x16x32_bf16 v[60:63], v[158:161], v[178:181], v[60:63]
	v_mfma_f32_16x16x32_bf16 v[56:59], v[170:173], v[178:181], v[56:59]
	v_mfma_f32_16x16x32_bf16 v[44:47], v[158:161], v[186:189], v[44:47]
	v_mfma_f32_16x16x32_bf16 v[40:43], v[170:173], v[186:189], v[40:43]
	v_mfma_f32_16x16x32_bf16 v[28:31], v[158:161], v[194:197], v[28:31]
	v_mfma_f32_16x16x32_bf16 v[24:27], v[170:173], v[194:197], v[24:27]
	v_mfma_f32_16x16x32_bf16 v[12:15], v[158:161], v[202:205], v[12:15]
	v_mfma_f32_16x16x32_bf16 v[8:11], v[170:173], v[202:205], v[8:11]
	s_setprio 0
	s_barrier
	s_add_u32 s44, s44, 0x20080
	s_addc_u32 s45, s45, 0
	s_add_i32 s50, s50, s63
	v_lshl_add_u64 v[146:147], s[44:45], 0, v[130:131]
	s_mov_b32 m0, s50
	s_nop 0
	global_load_lds_dwordx4 v[146:147], off
	v_lshl_add_u64 v[146:147], s[44:45], 0, v[134:135]
	s_add_i32 m0, s50, 0x2000
	s_nop 0
	global_load_lds_dwordx4 v[146:147], off
	s_waitcnt vmcnt(6)
	s_barrier
	s_setprio 1
	v_mfma_f32_16x16x32_bf16 v[52:55], v[210:213], v[174:177], v[52:55]
	v_mfma_f32_16x16x32_bf16 v[48:51], v[218:221], v[174:177], v[48:51]
	v_mfma_f32_16x16x32_bf16 v[36:39], v[210:213], v[182:185], v[36:39]
	v_mfma_f32_16x16x32_bf16 v[32:35], v[218:221], v[182:185], v[32:35]
	v_mfma_f32_16x16x32_bf16 v[20:23], v[210:213], v[190:193], v[20:23]
	v_mfma_f32_16x16x32_bf16 v[16:19], v[218:221], v[190:193], v[16:19]
	v_mfma_f32_16x16x32_bf16 v[4:7], v[210:213], v[198:201], v[4:7]
	v_mfma_f32_16x16x32_bf16 v[0:3], v[218:221], v[198:201], v[0:3]
	v_mfma_f32_16x16x32_bf16 v[52:55], v[214:217], v[178:181], v[52:55]
	v_mfma_f32_16x16x32_bf16 v[48:51], v[222:225], v[178:181], v[48:51]
	v_mfma_f32_16x16x32_bf16 v[36:39], v[214:217], v[186:189], v[36:39]
	v_mfma_f32_16x16x32_bf16 v[32:35], v[222:225], v[186:189], v[32:35]
	v_mfma_f32_16x16x32_bf16 v[20:23], v[214:217], v[194:197], v[20:23]
	v_mfma_f32_16x16x32_bf16 v[16:19], v[222:225], v[194:197], v[16:19]
	v_mfma_f32_16x16x32_bf16 v[4:7], v[214:217], v[202:205], v[4:7]
	v_mfma_f32_16x16x32_bf16 v[0:3], v[222:225], v[202:205], v[0:3]
	s_setprio 0
	s_add_i32 s80, s80, 2
	s_add_u32 s26, s26, 0x100
	s_addc_u32 s27, s27, 0
	s_add_u32 s69, s69, 0x100
	s_addc_u32 s79, s79, 0
	s_cmp_gt_u32 s80, 5
	s_barrier
	s_cbranch_scc0 .LBB0_364
	s_cmp_gt_i32 s64, 3
	v_lshl_add_u32 v146, s22, 8, v152
	s_cselect_b64 s[52:53], -1, 0
	v_pk_mul_f32 v[150:151], v[126:127], s[54:55] op_sel_hi:[1,0]
	v_pk_mul_f32 v[124:125], v[124:125], s[54:55] op_sel_hi:[1,0]
	v_pk_mul_f32 v[148:149], v[122:123], s[54:55] op_sel_hi:[1,0]
	v_pk_mul_f32 v[120:121], v[120:121], s[54:55] op_sel_hi:[1,0]
	v_pk_mul_f32 v[118:119], v[118:119], s[54:55] op_sel_hi:[1,0]
	v_pk_mul_f32 v[116:117], v[116:117], s[54:55] op_sel_hi:[1,0]
	v_pk_mul_f32 v[122:123], v[114:115], s[54:55] op_sel_hi:[1,0]
	v_pk_mul_f32 v[114:115], v[112:113], s[54:55] op_sel_hi:[1,0]
	s_mov_b64 s[22:23], -1
	s_and_b64 vcc, exec, s[52:53]
	v_ashrrev_i32_e32 v147, 31, v146
	s_cbranch_vccz .LBB0_367
	v_lshlrev_b64 v[112:113], 8, v[146:147]
	v_lshl_add_u64 v[112:113], v[136:137], 0, v[112:113]
	global_load_dwordx4 v[158:161], v[112:113], off offset:48
	global_load_dwordx4 v[162:165], v[112:113], off offset:32
	global_load_dwordx4 v[170:173], v[112:113], off offset:16
	global_load_dwordx4 v[174:177], v[112:113], off
	s_mov_b64 s[6:7], 0x1000
	v_lshl_add_u64 v[254:255], v[112:113], 0, s[6:7]
	global_load_dwordx4 v[228:231], v[254:255], off offset:48
	global_load_dwordx4 v[232:235], v[254:255], off offset:32
	global_load_dwordx4 v[236:239], v[254:255], off offset:16
	global_load_dwordx4 v[242:245], v[254:255], off
	s_mov_b64 s[22:23], 0
	s_waitcnt vmcnt(4)
	v_mul_f32_e32 v178, v150, v171
	v_mov_b32_e32 v127, v176
	v_mov_b32_e32 v176, v175
	v_mov_b32_e32 v126, v174
	v_pk_mul_f32 v[112:113], v[116:117], v[176:177]
	v_pk_mul_f32 v[166:167], v[124:125], v[176:177]
	v_mul_f32_e32 v174, v150, v170
	v_mul_f32_e32 v176, v118, v171
	v_mul_f32_e32 v170, v118, v170
	v_mov_b32_e32 v118, v151
	v_mov_b32_e32 v150, v119
	v_pk_mul_f32 v[180:181], v[118:119], v[172:173]
	v_pk_mul_f32 v[118:119], v[150:151], v[172:173]
	v_mov_b32_e32 v151, v164
	v_mov_b32_e32 v164, v163
	v_pk_fma_f32 v[124:125], v[124:125], v[126:127], v[112:113] neg_lo:[0,0,1] neg_hi:[0,0,1]
	v_mov_b32_e32 v171, v118
	v_mov_b32_e32 v179, v119
	v_pk_fma_f32 v[116:117], v[116:117], v[126:127], v[166:167]
	v_mov_b32_e32 v150, v162
	v_pk_mul_f32 v[126:127], v[114:115], v[164:165]
	v_pk_mul_f32 v[162:163], v[120:121], v[164:165]
	v_mul_f32_e32 v164, v148, v158
	v_mul_f32_e32 v166, v122, v159
	v_mul_f32_e32 v158, v122, v158
	v_mov_b32_e32 v122, v149
	v_pk_add_f32 v[118:119], v[170:171], v[178:179]
	v_mul_f32_e32 v170, v148, v159
	v_pk_mul_f32 v[172:173], v[122:123], v[160:161]
	v_mov_b32_e32 v148, v123
	v_mov_b32_e32 v175, v180
	v_mov_b32_e32 v177, v181
	v_mov_b32_e32 v165, v172
	v_mov_b32_e32 v167, v173
	v_pk_mul_f32 v[122:123], v[148:149], v[160:161]
	v_pk_add_f32 v[112:113], v[174:175], v[176:177] neg_lo:[0,1] neg_hi:[0,1]
	v_pk_fma_f32 v[120:121], v[120:121], v[150:151], v[126:127] neg_lo:[0,0,1] neg_hi:[0,0,1]
	v_pk_add_f32 v[126:127], v[164:165], v[166:167] neg_lo:[0,1] neg_hi:[0,1]
	v_mov_b32_e32 v159, v122
	v_mov_b32_e32 v171, v123
	v_pk_fma_f32 v[114:115], v[114:115], v[150:151], v[162:163]
	v_pk_add_f32 v[122:123], v[158:159], v[170:171]
	v_mov_b32_e32 v151, v113
	v_mov_b32_e32 v150, v112
	v_mov_b32_e32 v149, v127
	v_mov_b32_e32 v148, v126
; __device__ __forceinline__ u32x4 pack8(const f32x4& v0, const f32x4& v1) { u32x4 w; w.x = cvtpk(v0[0], v0[1]); w.y = cvtpk(v0[2], v0[3]); w.z = cvtpk(v1[0], v1[1]); w.w = cvtpk(v1[2], v1[3]); return w; }
;     __device__ __forceinline__ void operator()(const f32x4 (&acc)[2][2][4][2], const Unit& u, int wr, int wc, int fr, int fq) const {
;     ...
;             for (int m = 0; m < 4; ++m) { const int row = row0 + ai * HALF + m * 16; const float s = mult;
;                 f32x4 a0 = acc[ai][0][m][0] * s, a1 = acc[ai][0][m][1] * s, b0 = acc[ai][1][m][0] * s, b1 = acc[ai][1][m][1] * s;
;                 if (rope) { const f32x4* cp = (const f32x4*)(cs + (size_t)row * 64 + 16 * fq);
;                     const f32x4 c0 = cp[0], c1 = cp[1], c2 = cp[2], c3 = cp[3];
;                     f32x4 x0, x1, y0, y1;
;                     x0[0] = a0[0] * c0[0] - b0[0] * c0[1]; y0[0] = b0[0] * c0[0] + a0[0] * c0[1];
;                     x0[1] = a0[1] * c0[2] - b0[1] * c0[3]; y0[1] = b0[1] * c0[2] + a0[1] * c0[3];
;                     x0[2] = a0[2] * c1[0] - b0[2] * c1[1]; y0[2] = b0[2] * c1[0] + a0[2] * c1[1];
;                     x0[3] = a0[3] * c1[2] - b0[3] * c1[3]; y0[3] = b0[3] * c1[2] + a0[3] * c1[3];
;                     x1[0] = a1[0] * c2[0] - b1[0] * c2[1]; y1[0] = b1[0] * c2[0] + a1[0] * c2[1];
;                     x1[1] = a1[1] * c2[2] - b1[1] * c2[3]; y1[1] = b1[1] * c2[2] + a1[1] * c2[3];
;                     x1[2] = a1[2] * c3[0] - b1[2] * c3[1]; y1[2] = b1[2] * c3[0] + a1[2] * c3[1];
;                     x1[3] = a1[3] * c3[2] - b1[3] * c3[3]; y1[3] = b1[3] * c3[2] + a1[3] * c3[3];
;                     a0 = x0; a1 = x1; b0 = y0; b1 = y1; }
;                 bf16_t* rowp = O + (size_t)row * ldc + col0;
;                 *(u32x4*)(rowp) = pack8(a0, a1); *(u32x4*)(rowp + HALF) = pack8(b0, b1); }
.LBB0_367:
	v_mov_b64_e32 v[126:127], s[24:25]
	s_andn2_b64 vcc, exec, s[22:23]
	v_mad_u64_u32 v[126:127], s[22:23], v146, s78, v[126:127]
	v_mov_b32_e32 v158, v127
	v_lshl_or_b32 v112, s64, 8, v154
	v_mad_u64_u32 v[158:159], s[22:23], v147, s78, v[158:159]
	v_ashrrev_i32_e32 v113, 31, v112
	v_mov_b32_e32 v127, v158
	v_lshl_add_u64 v[158:159], v[112:113], 1, v[126:127]
	v_cvt_pk_bf16_f32 v116, v116, v117
	v_cvt_pk_bf16_f32 v117, v118, v119
	v_cvt_pk_bf16_f32 v118, v114, v115
	v_cvt_pk_bf16_f32 v119, v122, v123
	v_or_b32_e32 v114, 16, v146
	v_cvt_pk_bf16_f32 v124, v124, v125
	v_cvt_pk_bf16_f32 v125, v150, v151
	v_cvt_pk_bf16_f32 v126, v120, v121
	v_cvt_pk_bf16_f32 v127, v148, v149
	global_store_dwordx4 v[158:159], v[116:119], off offset:256
	v_pk_mul_f32 v[108:109], v[108:109], s[54:55] op_sel_hi:[1,0]
	v_pk_mul_f32 v[104:105], v[104:105], s[54:55] op_sel_hi:[1,0]
	v_pk_mul_f32 v[118:119], v[110:111], s[54:55] op_sel_hi:[1,0]
	v_pk_mul_f32 v[116:117], v[106:107], s[54:55] op_sel_hi:[1,0]
	v_pk_mul_f32 v[102:103], v[102:103], s[54:55] op_sel_hi:[1,0]
	v_pk_mul_f32 v[100:101], v[100:101], s[54:55] op_sel_hi:[1,0]
	v_pk_mul_f32 v[98:99], v[98:99], s[54:55] op_sel_hi:[1,0]
	v_pk_mul_f32 v[96:97], v[96:97], s[54:55] op_sel_hi:[1,0]
	s_mov_b64 s[22:23], -1
	s_and_b64 vcc, exec, s[52:53]
	v_ashrrev_i32_e32 v115, 31, v114
	global_store_dwordx4 v[158:159], v[124:127], off
	s_cbranch_vccz .LBB0_369
	v_lshlrev_b64 v[106:107], 8, v[114:115]
	v_lshl_add_u64 v[106:107], v[136:137], 0, v[106:107]
	s_mov_b64 s[22:23], 0
	s_waitcnt vmcnt(2)
	v_mov_b32_e32 v120, v228
	v_mov_b32_e32 v121, v229
	v_mov_b32_e32 v122, v230
	v_mov_b32_e32 v123, v231
	v_mov_b32_e32 v124, v232
	v_mov_b32_e32 v125, v233
	v_mov_b32_e32 v126, v234
	v_mov_b32_e32 v127, v235
	v_mov_b32_e32 v148, v236
	v_mov_b32_e32 v149, v237
	v_mov_b32_e32 v150, v238
	v_mov_b32_e32 v151, v239
	v_mov_b32_e32 v158, v242
	v_mov_b32_e32 v159, v243
	v_mov_b32_e32 v160, v244
	v_mov_b32_e32 v161, v245
	v_mul_f32_e32 v162, v102, v149
	v_mov_b32_e32 v111, v160
	v_mov_b32_e32 v160, v159
	v_mov_b32_e32 v110, v158
	v_pk_mul_f32 v[106:107], v[100:101], v[160:161]
	v_pk_mul_f32 v[158:159], v[108:109], v[160:161]
	v_mul_f32_e32 v160, v118, v148
	v_mul_f32_e32 v148, v102, v148
	v_mul_f32_e32 v164, v118, v149
	v_mov_b32_e32 v102, v119
	v_mov_b32_e32 v118, v103
	v_pk_mul_f32 v[166:167], v[102:103], v[150:151]
	v_pk_mul_f32 v[102:103], v[118:119], v[150:151]
	v_mov_b32_e32 v119, v126
	v_mov_b32_e32 v149, v102
	v_mov_b32_e32 v165, v103
	v_mov_b32_e32 v126, v125
	v_pk_fma_f32 v[108:109], v[108:109], v[110:111], v[106:107] neg_lo:[0,0,1] neg_hi:[0,0,1]
	v_pk_fma_f32 v[100:101], v[100:101], v[110:111], v[158:159]
	v_pk_add_f32 v[102:103], v[148:149], v[164:165]
	v_mov_b32_e32 v118, v124
	v_pk_mul_f32 v[110:111], v[96:97], v[126:127]
	v_pk_mul_f32 v[124:125], v[104:105], v[126:127]
	v_mul_f32_e32 v126, v116, v120
	v_mul_f32_e32 v148, v98, v121
	v_mul_f32_e32 v120, v98, v120
	v_mov_b32_e32 v98, v117
	v_mul_f32_e32 v150, v116, v121
	v_pk_mul_f32 v[158:159], v[98:99], v[122:123]
	v_mov_b32_e32 v116, v99
	v_mov_b32_e32 v161, v166
	v_mov_b32_e32 v163, v167
	v_mov_b32_e32 v127, v158
	v_mov_b32_e32 v149, v159
	v_pk_mul_f32 v[98:99], v[116:117], v[122:123]
	v_pk_add_f32 v[106:107], v[160:161], v[162:163] neg_lo:[0,1] neg_hi:[0,1]
	v_pk_fma_f32 v[104:105], v[104:105], v[118:119], v[110:111] neg_lo:[0,0,1] neg_hi:[0,0,1]
	v_pk_add_f32 v[110:111], v[126:127], v[148:149] neg_lo:[0,1] neg_hi:[0,1]
	v_mov_b32_e32 v121, v98
	v_mov_b32_e32 v151, v99
	v_pk_fma_f32 v[96:97], v[96:97], v[118:119], v[124:125]
	v_pk_add_f32 v[98:99], v[120:121], v[150:151]
	v_mov_b32_e32 v119, v107
	v_mov_b32_e32 v118, v106
	v_mov_b32_e32 v117, v111
	v_mov_b32_e32 v116, v110
.LBB0_369:
	v_mov_b64_e32 v[106:107], s[24:25]
	s_andn2_b64 vcc, exec, s[22:23]
	v_mad_u64_u32 v[106:107], s[22:23], v114, s78, v[106:107]
	v_mov_b32_e32 v110, v107
	v_mad_u64_u32 v[110:111], s[22:23], v115, s78, v[110:111]
	v_mov_b32_e32 v107, v110
	v_lshl_add_u64 v[110:111], v[112:113], 1, v[106:107]
	v_cvt_pk_bf16_f32 v100, v100, v101
	v_cvt_pk_bf16_f32 v101, v102, v103
	v_cvt_pk_bf16_f32 v102, v96, v97
	v_cvt_pk_bf16_f32 v103, v98, v99
	v_or_b32_e32 v96, 32, v146
	v_cvt_pk_bf16_f32 v106, v108, v109
	v_cvt_pk_bf16_f32 v107, v118, v119
	v_cvt_pk_bf16_f32 v108, v104, v105
	v_cvt_pk_bf16_f32 v109, v116, v117
	global_store_dwordx4 v[110:111], v[100:103], off offset:256
	v_pk_mul_f32 v[92:93], v[92:93], s[54:55] op_sel_hi:[1,0]
	v_pk_mul_f32 v[98:99], v[90:91], s[54:55] op_sel_hi:[1,0]
	v_pk_mul_f32 v[100:101], v[94:95], s[54:55] op_sel_hi:[1,0]
	v_pk_mul_f32 v[88:89], v[88:89], s[54:55] op_sel_hi:[1,0]
	v_pk_mul_f32 v[86:87], v[86:87], s[54:55] op_sel_hi:[1,0]
	v_pk_mul_f32 v[84:85], v[84:85], s[54:55] op_sel_hi:[1,0]
	v_pk_mul_f32 v[82:83], v[82:83], s[54:55] op_sel_hi:[1,0]
	v_pk_mul_f32 v[80:81], v[80:81], s[54:55] op_sel_hi:[1,0]
	s_mov_b64 s[22:23], -1
	s_and_b64 vcc, exec, s[52:53]
	v_ashrrev_i32_e32 v97, 31, v96
	global_store_dwordx4 v[110:111], v[106:109], off
	s_cbranch_vccz .LBB0_371
; __device__ __forceinline__ u32x4 pack8(const f32x4& v0, const f32x4& v1) { u32x4 w; w.x = cvtpk(v0[0], v0[1]); w.y = cvtpk(v0[2], v0[3]); w.z = cvtpk(v1[0], v1[1]); w.w = cvtpk(v1[2], v1[3]); return w; }
;     __device__ __forceinline__ void operator()(const f32x4 (&acc)[2][2][4][2], const Unit& u, int wr, int wc, int fr, int fq) const {
;     ...
;             for (int m = 0; m < 4; ++m) { const int row = row0 + ai * HALF + m * 16; const float s = mult;
;                 f32x4 a0 = acc[ai][0][m][0] * s, a1 = acc[ai][0][m][1] * s, b0 = acc[ai][1][m][0] * s, b1 = acc[ai][1][m][1] * s;
;                 if (rope) { const f32x4* cp = (const f32x4*)(cs + (size_t)row * 64 + 16 * fq);
;                     const f32x4 c0 = cp[0], c1 = cp[1], c2 = cp[2], c3 = cp[3];
;                     f32x4 x0, x1, y0, y1;
;                     x0[0] = a0[0] * c0[0] - b0[0] * c0[1]; y0[0] = b0[0] * c0[0] + a0[0] * c0[1];
;                     x0[1] = a0[1] * c0[2] - b0[1] * c0[3]; y0[1] = b0[1] * c0[2] + a0[1] * c0[3];
;                     x0[2] = a0[2] * c1[0] - b0[2] * c1[1]; y0[2] = b0[2] * c1[0] + a0[2] * c1[1];
;                     x0[3] = a0[3] * c1[2] - b0[3] * c1[3]; y0[3] = b0[3] * c1[2] + a0[3] * c1[3];
;                     x1[0] = a1[0] * c2[0] - b1[0] * c2[1]; y1[0] = b1[0] * c2[0] + a1[0] * c2[1];
;                     x1[1] = a1[1] * c2[2] - b1[1] * c2[3]; y1[1] = b1[1] * c2[2] + a1[1] * c2[3];
;                     x1[2] = a1[2] * c3[0] - b1[2] * c3[1]; y1[2] = b1[2] * c3[0] + a1[2] * c3[1];
;                     x1[3] = a1[3] * c3[2] - b1[3] * c3[3]; y1[3] = b1[3] * c3[2] + a1[3] * c3[3];
;                     a0 = x0; a1 = x1; b0 = y0; b1 = y1; }
;                 bf16_t* rowp = O + (size_t)row * ldc + col0;
;                 *(u32x4*)(rowp) = pack8(a0, a1); *(u32x4*)(rowp + HALF) = pack8(b0, b1); }
	v_lshlrev_b64 v[90:91], 8, v[96:97]
	v_lshl_add_u64 v[90:91], v[136:137], 0, v[90:91]
	global_load_dwordx4 v[102:105], v[90:91], off offset:48
	global_load_dwordx4 v[106:109], v[90:91], off offset:32
	global_load_dwordx4 v[114:117], v[90:91], off offset:16
	global_load_dwordx4 v[118:121], v[90:91], off
	s_mov_b64 s[6:7], 0x1000
	v_lshl_add_u64 v[254:255], v[90:91], 0, s[6:7]
	global_load_dwordx4 v[228:231], v[254:255], off offset:48
	global_load_dwordx4 v[232:235], v[254:255], off offset:32
	global_load_dwordx4 v[236:239], v[254:255], off offset:16
	global_load_dwordx4 v[242:245], v[254:255], off
	s_mov_b64 s[22:23], 0
	s_waitcnt vmcnt(4)
	v_mul_f32_e32 v122, v100, v115
	v_mov_b32_e32 v95, v120
	v_mov_b32_e32 v120, v119
	v_mov_b32_e32 v94, v118
	v_pk_mul_f32 v[90:91], v[84:85], v[120:121]
	v_pk_mul_f32 v[110:111], v[92:93], v[120:121]
	v_mul_f32_e32 v118, v100, v114
	v_mul_f32_e32 v120, v86, v115
	v_mul_f32_e32 v114, v86, v114
	v_mov_b32_e32 v86, v101
	v_mov_b32_e32 v100, v87
	v_pk_mul_f32 v[124:125], v[86:87], v[116:117]
	v_pk_mul_f32 v[86:87], v[100:101], v[116:117]
	v_mov_b32_e32 v101, v108
	v_mov_b32_e32 v108, v107
	v_pk_fma_f32 v[92:93], v[92:93], v[94:95], v[90:91] neg_lo:[0,0,1] neg_hi:[0,0,1]
	v_mov_b32_e32 v115, v86
	v_mov_b32_e32 v123, v87
	v_pk_fma_f32 v[84:85], v[84:85], v[94:95], v[110:111]
	v_mov_b32_e32 v100, v106
	v_pk_mul_f32 v[94:95], v[80:81], v[108:109]
	v_pk_mul_f32 v[106:107], v[88:89], v[108:109]
	v_mul_f32_e32 v108, v98, v102
	v_mul_f32_e32 v110, v82, v103
	v_mul_f32_e32 v102, v82, v102
	v_mov_b32_e32 v82, v99
	v_pk_add_f32 v[86:87], v[114:115], v[122:123]
	v_mul_f32_e32 v114, v98, v103
	v_pk_mul_f32 v[116:117], v[82:83], v[104:105]
	v_mov_b32_e32 v98, v83
	v_mov_b32_e32 v119, v124
	v_mov_b32_e32 v121, v125
	v_mov_b32_e32 v109, v116
	v_mov_b32_e32 v111, v117
	v_pk_mul_f32 v[82:83], v[98:99], v[104:105]
	v_pk_add_f32 v[90:91], v[118:119], v[120:121] neg_lo:[0,1] neg_hi:[0,1]
	v_pk_fma_f32 v[88:89], v[88:89], v[100:101], v[94:95] neg_lo:[0,0,1] neg_hi:[0,0,1]
	v_pk_add_f32 v[94:95], v[108:109], v[110:111] neg_lo:[0,1] neg_hi:[0,1]
	v_mov_b32_e32 v103, v82
	v_mov_b32_e32 v115, v83
	v_pk_fma_f32 v[80:81], v[80:81], v[100:101], v[106:107]
	v_pk_add_f32 v[82:83], v[102:103], v[114:115]
	v_mov_b32_e32 v101, v91
	v_mov_b32_e32 v100, v90
	v_mov_b32_e32 v99, v95
	v_mov_b32_e32 v98, v94
.LBB0_371:
	v_mov_b64_e32 v[90:91], s[24:25]
	s_andn2_b64 vcc, exec, s[22:23]
	v_mad_u64_u32 v[90:91], s[22:23], v96, s78, v[90:91]
	v_mov_b32_e32 v94, v91
	v_mad_u64_u32 v[94:95], s[22:23], v97, s78, v[94:95]
	v_mov_b32_e32 v91, v94
	v_lshl_add_u64 v[94:95], v[112:113], 1, v[90:91]
	v_cvt_pk_bf16_f32 v84, v84, v85
	v_cvt_pk_bf16_f32 v85, v86, v87
	v_cvt_pk_bf16_f32 v86, v80, v81
	v_cvt_pk_bf16_f32 v87, v82, v83
	v_or_b32_e32 v80, 48, v146
	v_cvt_pk_bf16_f32 v90, v92, v93
	v_cvt_pk_bf16_f32 v91, v100, v101
	v_cvt_pk_bf16_f32 v92, v88, v89
	v_cvt_pk_bf16_f32 v93, v98, v99
	global_store_dwordx4 v[94:95], v[84:87], off offset:256
	v_pk_mul_f32 v[76:77], v[76:77], s[54:55] op_sel_hi:[1,0]
	v_pk_mul_f32 v[82:83], v[74:75], s[54:55] op_sel_hi:[1,0]
	v_pk_mul_f32 v[84:85], v[78:79], s[54:55] op_sel_hi:[1,0]
	v_pk_mul_f32 v[72:73], v[72:73], s[54:55] op_sel_hi:[1,0]
	v_pk_mul_f32 v[70:71], v[70:71], s[54:55] op_sel_hi:[1,0]
	v_pk_mul_f32 v[68:69], v[68:69], s[54:55] op_sel_hi:[1,0]
	v_pk_mul_f32 v[66:67], v[66:67], s[54:55] op_sel_hi:[1,0]
	v_pk_mul_f32 v[64:65], v[64:65], s[54:55] op_sel_hi:[1,0]
	s_mov_b64 s[22:23], -1
	s_and_b64 vcc, exec, s[52:53]
	v_ashrrev_i32_e32 v81, 31, v80
	global_store_dwordx4 v[94:95], v[90:93], off
	s_cbranch_vccz .LBB0_373
	v_lshlrev_b64 v[74:75], 8, v[80:81]
	v_lshl_add_u64 v[74:75], v[136:137], 0, v[74:75]
	s_mov_b64 s[22:23], 0
	s_waitcnt vmcnt(2)
	v_mov_b32_e32 v86, v228
	v_mov_b32_e32 v87, v229
	v_mov_b32_e32 v88, v230
	v_mov_b32_e32 v89, v231
	v_mov_b32_e32 v90, v232
	v_mov_b32_e32 v91, v233
	v_mov_b32_e32 v92, v234
	v_mov_b32_e32 v93, v235
	v_mov_b32_e32 v94, v236
	v_mov_b32_e32 v95, v237
	v_mov_b32_e32 v96, v238
	v_mov_b32_e32 v97, v239
	v_mov_b32_e32 v98, v242
	v_mov_b32_e32 v99, v243
	v_mov_b32_e32 v100, v244
	v_mov_b32_e32 v101, v245
	v_mul_f32_e32 v102, v70, v95
	v_mov_b32_e32 v79, v100
	v_mov_b32_e32 v100, v99
	v_mov_b32_e32 v78, v98
	v_pk_mul_f32 v[74:75], v[68:69], v[100:101]
	v_pk_mul_f32 v[98:99], v[76:77], v[100:101]
	v_mul_f32_e32 v100, v84, v94
	v_mul_f32_e32 v94, v70, v94
	v_mul_f32_e32 v104, v84, v95
	v_mov_b32_e32 v70, v85
	v_mov_b32_e32 v84, v71
	v_pk_mul_f32 v[106:107], v[70:71], v[96:97]
	v_pk_mul_f32 v[70:71], v[84:85], v[96:97]
	v_mov_b32_e32 v85, v92
	v_mov_b32_e32 v95, v70
	v_mov_b32_e32 v105, v71
	v_mov_b32_e32 v92, v91
	v_pk_fma_f32 v[76:77], v[76:77], v[78:79], v[74:75] neg_lo:[0,0,1] neg_hi:[0,0,1]
	v_pk_fma_f32 v[68:69], v[68:69], v[78:79], v[98:99]
	v_pk_add_f32 v[70:71], v[94:95], v[104:105]
	v_mov_b32_e32 v84, v90
	v_pk_mul_f32 v[78:79], v[64:65], v[92:93]
	v_pk_mul_f32 v[90:91], v[72:73], v[92:93]
	v_mul_f32_e32 v92, v82, v86
	v_mul_f32_e32 v94, v66, v87
	v_mul_f32_e32 v86, v66, v86
	v_mov_b32_e32 v66, v83
	v_mul_f32_e32 v96, v82, v87
	v_pk_mul_f32 v[98:99], v[66:67], v[88:89]
	v_mov_b32_e32 v82, v67
	v_mov_b32_e32 v101, v106
	v_mov_b32_e32 v103, v107
	v_mov_b32_e32 v93, v98
	v_mov_b32_e32 v95, v99
	v_pk_mul_f32 v[66:67], v[82:83], v[88:89]
	v_pk_add_f32 v[74:75], v[100:101], v[102:103] neg_lo:[0,1] neg_hi:[0,1]
	v_pk_fma_f32 v[72:73], v[72:73], v[84:85], v[78:79] neg_lo:[0,0,1] neg_hi:[0,0,1]
	v_pk_add_f32 v[78:79], v[92:93], v[94:95] neg_lo:[0,1] neg_hi:[0,1]
	v_mov_b32_e32 v87, v66
	v_mov_b32_e32 v97, v67
	v_pk_fma_f32 v[64:65], v[64:65], v[84:85], v[90:91]
	v_pk_add_f32 v[66:67], v[86:87], v[96:97]
	v_mov_b32_e32 v85, v75
	v_mov_b32_e32 v84, v74
	v_mov_b32_e32 v83, v79
	v_mov_b32_e32 v82, v78
; __device__ __forceinline__ u32x4 pack8(const f32x4& v0, const f32x4& v1) { u32x4 w; w.x = cvtpk(v0[0], v0[1]); w.y = cvtpk(v0[2], v0[3]); w.z = cvtpk(v1[0], v1[1]); w.w = cvtpk(v1[2], v1[3]); return w; }
;     __device__ __forceinline__ void operator()(const f32x4 (&acc)[2][2][4][2], const Unit& u, int wr, int wc, int fr, int fq) const {
;     ...
;             for (int m = 0; m < 4; ++m) { const int row = row0 + ai * HALF + m * 16; const float s = mult;
;                 f32x4 a0 = acc[ai][0][m][0] * s, a1 = acc[ai][0][m][1] * s, b0 = acc[ai][1][m][0] * s, b1 = acc[ai][1][m][1] * s;
;                 if (rope) { const f32x4* cp = (const f32x4*)(cs + (size_t)row * 64 + 16 * fq);
;                     const f32x4 c0 = cp[0], c1 = cp[1], c2 = cp[2], c3 = cp[3];
;                     f32x4 x0, x1, y0, y1;
;                     x0[0] = a0[0] * c0[0] - b0[0] * c0[1]; y0[0] = b0[0] * c0[0] + a0[0] * c0[1];
;                     x0[1] = a0[1] * c0[2] - b0[1] * c0[3]; y0[1] = b0[1] * c0[2] + a0[1] * c0[3];
;                     x0[2] = a0[2] * c1[0] - b0[2] * c1[1]; y0[2] = b0[2] * c1[0] + a0[2] * c1[1];
;                     x0[3] = a0[3] * c1[2] - b0[3] * c1[3]; y0[3] = b0[3] * c1[2] + a0[3] * c1[3];
;                     x1[0] = a1[0] * c2[0] - b1[0] * c2[1]; y1[0] = b1[0] * c2[0] + a1[0] * c2[1];
;                     x1[1] = a1[1] * c2[2] - b1[1] * c2[3]; y1[1] = b1[1] * c2[2] + a1[1] * c2[3];
;                     x1[2] = a1[2] * c3[0] - b1[2] * c3[1]; y1[2] = b1[2] * c3[0] + a1[2] * c3[1];
;                     x1[3] = a1[3] * c3[2] - b1[3] * c3[3]; y1[3] = b1[3] * c3[2] + a1[3] * c3[3];
;                     a0 = x0; a1 = x1; b0 = y0; b1 = y1; }
;                 bf16_t* rowp = O + (size_t)row * ldc + col0;
;                 *(u32x4*)(rowp) = pack8(a0, a1); *(u32x4*)(rowp + HALF) = pack8(b0, b1); }
.LBB0_373:
	v_mov_b64_e32 v[74:75], s[24:25]
	s_andn2_b64 vcc, exec, s[22:23]
	v_mad_u64_u32 v[74:75], s[22:23], v80, s78, v[74:75]
	v_mov_b32_e32 v78, v75
	v_mad_u64_u32 v[78:79], s[22:23], v81, s78, v[78:79]
	v_mov_b32_e32 v75, v78
	v_lshl_add_u64 v[78:79], v[112:113], 1, v[74:75]
	v_cvt_pk_bf16_f32 v68, v68, v69
	v_cvt_pk_bf16_f32 v69, v70, v71
	v_cvt_pk_bf16_f32 v70, v64, v65
	v_cvt_pk_bf16_f32 v71, v66, v67
	v_add_u32_e32 v64, 0x80, v146
	v_cvt_pk_bf16_f32 v74, v76, v77
	v_cvt_pk_bf16_f32 v75, v84, v85
	v_cvt_pk_bf16_f32 v76, v72, v73
	v_cvt_pk_bf16_f32 v77, v82, v83
	global_store_dwordx4 v[78:79], v[68:71], off offset:256
	v_pk_mul_f32 v[60:61], v[60:61], s[54:55] op_sel_hi:[1,0]
	v_pk_mul_f32 v[66:67], v[58:59], s[54:55] op_sel_hi:[1,0]
	v_pk_mul_f32 v[68:69], v[62:63], s[54:55] op_sel_hi:[1,0]
	v_pk_mul_f32 v[56:57], v[56:57], s[54:55] op_sel_hi:[1,0]
	v_pk_mul_f32 v[54:55], v[54:55], s[54:55] op_sel_hi:[1,0]
	v_pk_mul_f32 v[52:53], v[52:53], s[54:55] op_sel_hi:[1,0]
	v_pk_mul_f32 v[50:51], v[50:51], s[54:55] op_sel_hi:[1,0]
	v_pk_mul_f32 v[48:49], v[48:49], s[54:55] op_sel_hi:[1,0]
	s_mov_b64 s[22:23], -1
	s_and_b64 vcc, exec, s[52:53]
	v_ashrrev_i32_e32 v65, 31, v64
	global_store_dwordx4 v[78:79], v[74:77], off
	s_cbranch_vccz .LBB0_375
	v_lshlrev_b64 v[58:59], 8, v[64:65]
	v_lshl_add_u64 v[58:59], v[136:137], 0, v[58:59]
	global_load_dwordx4 v[70:73], v[58:59], off offset:48
	global_load_dwordx4 v[74:77], v[58:59], off offset:32
	global_load_dwordx4 v[78:81], v[58:59], off offset:16
	global_load_dwordx4 v[82:85], v[58:59], off
	s_mov_b64 s[6:7], 0x1000
	v_lshl_add_u64 v[254:255], v[58:59], 0, s[6:7]
	global_load_dwordx4 v[228:231], v[254:255], off offset:48
	global_load_dwordx4 v[232:235], v[254:255], off offset:32
	global_load_dwordx4 v[236:239], v[254:255], off offset:16
	global_load_dwordx4 v[242:245], v[254:255], off
	s_mov_b64 s[22:23], 0
	s_waitcnt vmcnt(4)
	v_mul_f32_e32 v86, v54, v79
	v_mov_b32_e32 v63, v84
	v_mov_b32_e32 v84, v83
	v_mov_b32_e32 v62, v82
	v_pk_mul_f32 v[58:59], v[52:53], v[84:85]
	v_pk_mul_f32 v[82:83], v[60:61], v[84:85]
	v_mul_f32_e32 v84, v68, v78
	v_mul_f32_e32 v78, v54, v78
	v_mul_f32_e32 v88, v68, v79
	v_mov_b32_e32 v54, v69
	v_mov_b32_e32 v68, v55
	v_pk_mul_f32 v[90:91], v[54:55], v[80:81]
	v_pk_mul_f32 v[54:55], v[68:69], v[80:81]
	v_mov_b32_e32 v69, v76
	v_mov_b32_e32 v79, v54
	v_mov_b32_e32 v89, v55
	v_mov_b32_e32 v76, v75
	v_pk_fma_f32 v[60:61], v[60:61], v[62:63], v[58:59] neg_lo:[0,0,1] neg_hi:[0,0,1]
	v_pk_fma_f32 v[52:53], v[52:53], v[62:63], v[82:83]
	v_pk_add_f32 v[54:55], v[78:79], v[88:89]
	v_mov_b32_e32 v68, v74
	v_pk_mul_f32 v[62:63], v[48:49], v[76:77]
	v_pk_mul_f32 v[74:75], v[56:57], v[76:77]
	v_mul_f32_e32 v76, v66, v70
	v_mul_f32_e32 v78, v50, v71
	v_mul_f32_e32 v70, v50, v70
	v_mov_b32_e32 v50, v67
	v_mul_f32_e32 v80, v66, v71
	v_pk_mul_f32 v[82:83], v[50:51], v[72:73]
	v_mov_b32_e32 v66, v51
	v_mov_b32_e32 v85, v90
	v_mov_b32_e32 v87, v91
	v_mov_b32_e32 v77, v82
	v_mov_b32_e32 v79, v83
	v_pk_mul_f32 v[50:51], v[66:67], v[72:73]
	v_pk_add_f32 v[58:59], v[84:85], v[86:87] neg_lo:[0,1] neg_hi:[0,1]
	v_pk_fma_f32 v[56:57], v[56:57], v[68:69], v[62:63] neg_lo:[0,0,1] neg_hi:[0,0,1]
	v_pk_add_f32 v[62:63], v[76:77], v[78:79] neg_lo:[0,1] neg_hi:[0,1]
	v_mov_b32_e32 v71, v50
	v_mov_b32_e32 v81, v51
	v_pk_fma_f32 v[48:49], v[48:49], v[68:69], v[74:75]
	v_pk_add_f32 v[50:51], v[70:71], v[80:81]
	v_mov_b32_e32 v69, v59
	v_mov_b32_e32 v68, v58
	v_mov_b32_e32 v67, v63
	v_mov_b32_e32 v66, v62
.LBB0_375:
	v_mov_b64_e32 v[58:59], s[24:25]
	s_andn2_b64 vcc, exec, s[22:23]
	v_mad_u64_u32 v[58:59], s[22:23], v64, s78, v[58:59]
	v_mov_b32_e32 v62, v59
	v_mad_u64_u32 v[62:63], s[22:23], v65, s78, v[62:63]
	v_mov_b32_e32 v59, v62
	v_lshl_add_u64 v[62:63], v[112:113], 1, v[58:59]
	v_cvt_pk_bf16_f32 v52, v52, v53
	v_cvt_pk_bf16_f32 v53, v54, v55
	v_cvt_pk_bf16_f32 v54, v48, v49
	v_cvt_pk_bf16_f32 v55, v50, v51
	v_add_u32_e32 v48, 0x90, v146
	v_cvt_pk_bf16_f32 v58, v60, v61
	v_cvt_pk_bf16_f32 v59, v68, v69
	v_cvt_pk_bf16_f32 v60, v56, v57
	v_cvt_pk_bf16_f32 v61, v66, v67
	global_store_dwordx4 v[62:63], v[52:55], off offset:256
	v_pk_mul_f32 v[44:45], v[44:45], s[54:55] op_sel_hi:[1,0]
	v_pk_mul_f32 v[50:51], v[42:43], s[54:55] op_sel_hi:[1,0]
	v_pk_mul_f32 v[52:53], v[46:47], s[54:55] op_sel_hi:[1,0]
	v_pk_mul_f32 v[40:41], v[40:41], s[54:55] op_sel_hi:[1,0]
	v_pk_mul_f32 v[38:39], v[38:39], s[54:55] op_sel_hi:[1,0]
	v_pk_mul_f32 v[36:37], v[36:37], s[54:55] op_sel_hi:[1,0]
	v_pk_mul_f32 v[34:35], v[34:35], s[54:55] op_sel_hi:[1,0]
	v_pk_mul_f32 v[32:33], v[32:33], s[54:55] op_sel_hi:[1,0]
	s_mov_b64 s[22:23], -1
	s_and_b64 vcc, exec, s[52:53]
	v_ashrrev_i32_e32 v49, 31, v48
	global_store_dwordx4 v[62:63], v[58:61], off
	s_cbranch_vccz .LBB0_377
	v_lshlrev_b64 v[42:43], 8, v[48:49]
	v_lshl_add_u64 v[42:43], v[136:137], 0, v[42:43]
	s_mov_b64 s[22:23], 0
	s_waitcnt vmcnt(2)
	v_mov_b32_e32 v54, v228
	v_mov_b32_e32 v55, v229
	v_mov_b32_e32 v56, v230
	v_mov_b32_e32 v57, v231
	v_mov_b32_e32 v58, v232
	v_mov_b32_e32 v59, v233
	v_mov_b32_e32 v60, v234
	v_mov_b32_e32 v61, v235
	v_mov_b32_e32 v62, v236
	v_mov_b32_e32 v63, v237
	v_mov_b32_e32 v64, v238
	v_mov_b32_e32 v65, v239
	v_mov_b32_e32 v66, v242
	v_mov_b32_e32 v67, v243
	v_mov_b32_e32 v68, v244
	v_mov_b32_e32 v69, v245
	v_mul_f32_e32 v70, v38, v63
	v_mov_b32_e32 v47, v68
	v_mov_b32_e32 v68, v67
	v_mov_b32_e32 v46, v66
	v_pk_mul_f32 v[42:43], v[36:37], v[68:69]
	v_pk_mul_f32 v[66:67], v[44:45], v[68:69]
	v_mul_f32_e32 v68, v52, v62
	v_mul_f32_e32 v62, v38, v62
	v_mul_f32_e32 v72, v52, v63
	v_mov_b32_e32 v38, v53
	v_mov_b32_e32 v52, v39
	v_pk_mul_f32 v[74:75], v[38:39], v[64:65]
	v_pk_mul_f32 v[38:39], v[52:53], v[64:65]
	v_mov_b32_e32 v53, v60
	v_mov_b32_e32 v63, v38
	v_mov_b32_e32 v73, v39
	v_mov_b32_e32 v60, v59
	v_pk_fma_f32 v[44:45], v[44:45], v[46:47], v[42:43] neg_lo:[0,0,1] neg_hi:[0,0,1]
	v_pk_fma_f32 v[36:37], v[36:37], v[46:47], v[66:67]
	v_pk_add_f32 v[38:39], v[62:63], v[72:73]
	v_mov_b32_e32 v52, v58
	v_pk_mul_f32 v[46:47], v[32:33], v[60:61]
	v_pk_mul_f32 v[58:59], v[40:41], v[60:61]
	v_mul_f32_e32 v60, v50, v54
	v_mul_f32_e32 v62, v34, v55
	v_mul_f32_e32 v54, v34, v54
	v_mov_b32_e32 v34, v51
	v_mul_f32_e32 v64, v50, v55
	v_pk_mul_f32 v[66:67], v[34:35], v[56:57]
	v_mov_b32_e32 v50, v35
	v_mov_b32_e32 v69, v74
	v_mov_b32_e32 v71, v75
	v_mov_b32_e32 v61, v66
	v_mov_b32_e32 v63, v67
	v_pk_mul_f32 v[34:35], v[50:51], v[56:57]
	v_pk_add_f32 v[42:43], v[68:69], v[70:71] neg_lo:[0,1] neg_hi:[0,1]
	v_pk_fma_f32 v[40:41], v[40:41], v[52:53], v[46:47] neg_lo:[0,0,1] neg_hi:[0,0,1]
	v_pk_add_f32 v[46:47], v[60:61], v[62:63] neg_lo:[0,1] neg_hi:[0,1]
	v_mov_b32_e32 v55, v34
	v_mov_b32_e32 v65, v35
	v_pk_fma_f32 v[32:33], v[32:33], v[52:53], v[58:59]
	v_pk_add_f32 v[34:35], v[54:55], v[64:65]
	v_mov_b32_e32 v53, v43
	v_mov_b32_e32 v52, v42
	v_mov_b32_e32 v51, v47
	v_mov_b32_e32 v50, v46
; __device__ __forceinline__ u32x4 pack8(const f32x4& v0, const f32x4& v1) { u32x4 w; w.x = cvtpk(v0[0], v0[1]); w.y = cvtpk(v0[2], v0[3]); w.z = cvtpk(v1[0], v1[1]); w.w = cvtpk(v1[2], v1[3]); return w; }
;     __device__ __forceinline__ void operator()(const f32x4 (&acc)[2][2][4][2], const Unit& u, int wr, int wc, int fr, int fq) const {
;     ...
;             for (int m = 0; m < 4; ++m) { const int row = row0 + ai * HALF + m * 16; const float s = mult;
;                 f32x4 a0 = acc[ai][0][m][0] * s, a1 = acc[ai][0][m][1] * s, b0 = acc[ai][1][m][0] * s, b1 = acc[ai][1][m][1] * s;
;                 if (rope) { const f32x4* cp = (const f32x4*)(cs + (size_t)row * 64 + 16 * fq);
;                     const f32x4 c0 = cp[0], c1 = cp[1], c2 = cp[2], c3 = cp[3];
;                     f32x4 x0, x1, y0, y1;
;                     x0[0] = a0[0] * c0[0] - b0[0] * c0[1]; y0[0] = b0[0] * c0[0] + a0[0] * c0[1];
;                     x0[1] = a0[1] * c0[2] - b0[1] * c0[3]; y0[1] = b0[1] * c0[2] + a0[1] * c0[3];
;                     x0[2] = a0[2] * c1[0] - b0[2] * c1[1]; y0[2] = b0[2] * c1[0] + a0[2] * c1[1];
;                     x0[3] = a0[3] * c1[2] - b0[3] * c1[3]; y0[3] = b0[3] * c1[2] + a0[3] * c1[3];
;                     x1[0] = a1[0] * c2[0] - b1[0] * c2[1]; y1[0] = b1[0] * c2[0] + a1[0] * c2[1];
;                     x1[1] = a1[1] * c2[2] - b1[1] * c2[3]; y1[1] = b1[1] * c2[2] + a1[1] * c2[3];
;                     x1[2] = a1[2] * c3[0] - b1[2] * c3[1]; y1[2] = b1[2] * c3[0] + a1[2] * c3[1];
;                     x1[3] = a1[3] * c3[2] - b1[3] * c3[3]; y1[3] = b1[3] * c3[2] + a1[3] * c3[3];
;                     a0 = x0; a1 = x1; b0 = y0; b1 = y1; }
;                 bf16_t* rowp = O + (size_t)row * ldc + col0;
;                 *(u32x4*)(rowp) = pack8(a0, a1); *(u32x4*)(rowp + HALF) = pack8(b0, b1); }
.LBB0_377:
	v_mov_b64_e32 v[42:43], s[24:25]
	s_andn2_b64 vcc, exec, s[22:23]
	v_mad_u64_u32 v[42:43], s[22:23], v48, s78, v[42:43]
	v_mov_b32_e32 v46, v43
	v_mad_u64_u32 v[46:47], s[22:23], v49, s78, v[46:47]
	v_mov_b32_e32 v43, v46
	v_lshl_add_u64 v[46:47], v[112:113], 1, v[42:43]
	v_cvt_pk_bf16_f32 v36, v36, v37
	v_cvt_pk_bf16_f32 v37, v38, v39
	v_cvt_pk_bf16_f32 v38, v32, v33
	v_cvt_pk_bf16_f32 v39, v34, v35
	v_add_u32_e32 v32, 0xa0, v146
	v_cvt_pk_bf16_f32 v42, v44, v45
	v_cvt_pk_bf16_f32 v43, v52, v53
	v_cvt_pk_bf16_f32 v44, v40, v41
	v_cvt_pk_bf16_f32 v45, v50, v51
	global_store_dwordx4 v[46:47], v[36:39], off offset:256
	v_pk_mul_f32 v[28:29], v[28:29], s[54:55] op_sel_hi:[1,0]
	v_pk_mul_f32 v[34:35], v[26:27], s[54:55] op_sel_hi:[1,0]
	v_pk_mul_f32 v[36:37], v[30:31], s[54:55] op_sel_hi:[1,0]
	v_pk_mul_f32 v[24:25], v[24:25], s[54:55] op_sel_hi:[1,0]
	v_pk_mul_f32 v[22:23], v[22:23], s[54:55] op_sel_hi:[1,0]
	v_pk_mul_f32 v[20:21], v[20:21], s[54:55] op_sel_hi:[1,0]
	v_pk_mul_f32 v[18:19], v[18:19], s[54:55] op_sel_hi:[1,0]
	v_pk_mul_f32 v[16:17], v[16:17], s[54:55] op_sel_hi:[1,0]
	s_mov_b64 s[22:23], -1
	s_and_b64 vcc, exec, s[52:53]
	v_ashrrev_i32_e32 v33, 31, v32
	global_store_dwordx4 v[46:47], v[42:45], off
	s_cbranch_vccz .LBB0_379
	v_lshlrev_b64 v[26:27], 8, v[32:33]
	v_lshl_add_u64 v[26:27], v[136:137], 0, v[26:27]
	global_load_dwordx4 v[38:41], v[26:27], off offset:48
	global_load_dwordx4 v[42:45], v[26:27], off offset:32
	global_load_dwordx4 v[46:49], v[26:27], off offset:16
	global_load_dwordx4 v[50:53], v[26:27], off
	s_mov_b64 s[6:7], 0x1000
	v_lshl_add_u64 v[254:255], v[26:27], 0, s[6:7]
	global_load_dwordx4 v[228:231], v[254:255], off offset:48
	global_load_dwordx4 v[232:235], v[254:255], off offset:32
	global_load_dwordx4 v[236:239], v[254:255], off offset:16
	global_load_dwordx4 v[242:245], v[254:255], off
	s_mov_b64 s[22:23], 0
	s_waitcnt vmcnt(4)
	v_mul_f32_e32 v54, v22, v47
	v_mov_b32_e32 v31, v52
	v_mov_b32_e32 v52, v51
	v_mov_b32_e32 v30, v50
	v_pk_mul_f32 v[26:27], v[20:21], v[52:53]
	v_pk_mul_f32 v[50:51], v[28:29], v[52:53]
	v_mul_f32_e32 v52, v36, v46
	v_mul_f32_e32 v46, v22, v46
	v_mul_f32_e32 v56, v36, v47
	v_mov_b32_e32 v22, v37
	v_mov_b32_e32 v36, v23
	v_pk_mul_f32 v[58:59], v[22:23], v[48:49]
	v_pk_mul_f32 v[22:23], v[36:37], v[48:49]
	v_mov_b32_e32 v37, v44
	v_mov_b32_e32 v47, v22
	v_mov_b32_e32 v57, v23
	v_mov_b32_e32 v44, v43
	v_pk_fma_f32 v[28:29], v[28:29], v[30:31], v[26:27] neg_lo:[0,0,1] neg_hi:[0,0,1]
	v_pk_fma_f32 v[20:21], v[20:21], v[30:31], v[50:51]
	v_pk_add_f32 v[22:23], v[46:47], v[56:57]
	v_mov_b32_e32 v36, v42
	v_pk_mul_f32 v[30:31], v[16:17], v[44:45]
	v_pk_mul_f32 v[42:43], v[24:25], v[44:45]
	v_mul_f32_e32 v44, v34, v38
	v_mul_f32_e32 v46, v18, v39
	v_mul_f32_e32 v38, v18, v38
	v_mov_b32_e32 v18, v35
	v_mul_f32_e32 v48, v34, v39
	v_pk_mul_f32 v[50:51], v[18:19], v[40:41]
	v_mov_b32_e32 v34, v19
	v_mov_b32_e32 v53, v58
	v_mov_b32_e32 v55, v59
	v_mov_b32_e32 v45, v50
	v_mov_b32_e32 v47, v51
	v_pk_mul_f32 v[18:19], v[34:35], v[40:41]
	v_pk_add_f32 v[26:27], v[52:53], v[54:55] neg_lo:[0,1] neg_hi:[0,1]
	v_pk_fma_f32 v[24:25], v[24:25], v[36:37], v[30:31] neg_lo:[0,0,1] neg_hi:[0,0,1]
	v_pk_add_f32 v[30:31], v[44:45], v[46:47] neg_lo:[0,1] neg_hi:[0,1]
	v_mov_b32_e32 v39, v18
	v_mov_b32_e32 v49, v19
	v_pk_fma_f32 v[16:17], v[16:17], v[36:37], v[42:43]
	v_pk_add_f32 v[18:19], v[38:39], v[48:49]
	v_mov_b32_e32 v37, v27
	v_mov_b32_e32 v36, v26
	v_mov_b32_e32 v35, v31
	v_mov_b32_e32 v34, v30
.LBB0_379:
	v_mov_b64_e32 v[26:27], s[24:25]
	s_andn2_b64 vcc, exec, s[22:23]
	v_mad_u64_u32 v[26:27], s[22:23], v32, s78, v[26:27]
	v_mov_b32_e32 v30, v27
	v_mad_u64_u32 v[30:31], s[22:23], v33, s78, v[30:31]
	v_mov_b32_e32 v27, v30
	v_lshl_add_u64 v[30:31], v[112:113], 1, v[26:27]
	v_cvt_pk_bf16_f32 v20, v20, v21
	v_cvt_pk_bf16_f32 v21, v22, v23
	v_cvt_pk_bf16_f32 v22, v16, v17
	v_cvt_pk_bf16_f32 v23, v18, v19
	v_add_u32_e32 v16, 0xb0, v146
	v_cvt_pk_bf16_f32 v26, v28, v29
	v_cvt_pk_bf16_f32 v27, v36, v37
	v_cvt_pk_bf16_f32 v28, v24, v25
	v_cvt_pk_bf16_f32 v29, v34, v35
	global_store_dwordx4 v[30:31], v[20:23], off offset:256
	v_pk_mul_f32 v[12:13], v[12:13], s[54:55] op_sel_hi:[1,0]
	v_pk_mul_f32 v[18:19], v[10:11], s[54:55] op_sel_hi:[1,0]
	v_pk_mul_f32 v[20:21], v[14:15], s[54:55] op_sel_hi:[1,0]
	v_pk_mul_f32 v[8:9], v[8:9], s[54:55] op_sel_hi:[1,0]
	v_pk_mul_f32 v[6:7], v[6:7], s[54:55] op_sel_hi:[1,0]
	v_pk_mul_f32 v[4:5], v[4:5], s[54:55] op_sel_hi:[1,0]
	v_pk_mul_f32 v[2:3], v[2:3], s[54:55] op_sel_hi:[1,0]
	v_pk_mul_f32 v[0:1], v[0:1], s[54:55] op_sel_hi:[1,0]
	s_mov_b64 s[22:23], -1
	s_and_b64 vcc, exec, s[52:53]
	v_ashrrev_i32_e32 v17, 31, v16
	global_store_dwordx4 v[30:31], v[26:29], off
	s_cbranch_vccz .LBB0_360
	v_lshlrev_b64 v[10:11], 8, v[16:17]
	v_lshl_add_u64 v[10:11], v[136:137], 0, v[10:11]
	s_mov_b64 s[22:23], 0
	s_waitcnt vmcnt(2)
	v_mov_b32_e32 v22, v228
	v_mov_b32_e32 v23, v229
	v_mov_b32_e32 v24, v230
	v_mov_b32_e32 v25, v231
	v_mov_b32_e32 v26, v232
	v_mov_b32_e32 v27, v233
	v_mov_b32_e32 v28, v234
	v_mov_b32_e32 v29, v235
	v_mov_b32_e32 v30, v236
	v_mov_b32_e32 v31, v237
	v_mov_b32_e32 v32, v238
	v_mov_b32_e32 v33, v239
	v_mov_b32_e32 v34, v242
	v_mov_b32_e32 v35, v243
	v_mov_b32_e32 v36, v244
	v_mov_b32_e32 v37, v245
	v_mul_f32_e32 v38, v6, v31
	v_mov_b32_e32 v15, v36
	v_mov_b32_e32 v36, v35
	v_mov_b32_e32 v14, v34
	v_pk_mul_f32 v[10:11], v[4:5], v[36:37]
	v_pk_mul_f32 v[34:35], v[12:13], v[36:37]
	v_mul_f32_e32 v36, v20, v30
	v_mul_f32_e32 v30, v6, v30
	v_mul_f32_e32 v40, v20, v31
	v_mov_b32_e32 v6, v21
	v_mov_b32_e32 v20, v7
	v_pk_mul_f32 v[42:43], v[6:7], v[32:33]
	v_pk_mul_f32 v[6:7], v[20:21], v[32:33]
	v_mov_b32_e32 v21, v28
	v_mov_b32_e32 v31, v6
	v_mov_b32_e32 v41, v7
	v_mov_b32_e32 v28, v27
	v_pk_fma_f32 v[12:13], v[12:13], v[14:15], v[10:11] neg_lo:[0,0,1] neg_hi:[0,0,1]
	v_pk_fma_f32 v[4:5], v[4:5], v[14:15], v[34:35]
	v_pk_add_f32 v[6:7], v[30:31], v[40:41]
	v_mov_b32_e32 v20, v26
	v_pk_mul_f32 v[14:15], v[0:1], v[28:29]
	v_pk_mul_f32 v[26:27], v[8:9], v[28:29]
	v_mul_f32_e32 v28, v18, v22
	v_mul_f32_e32 v30, v2, v23
	v_mul_f32_e32 v22, v2, v22
	v_mov_b32_e32 v2, v19
	v_mul_f32_e32 v32, v18, v23
	v_pk_mul_f32 v[34:35], v[2:3], v[24:25]
	v_mov_b32_e32 v18, v3
	v_mov_b32_e32 v37, v42
	v_mov_b32_e32 v39, v43
	v_mov_b32_e32 v29, v34
	v_mov_b32_e32 v31, v35
	v_pk_mul_f32 v[2:3], v[18:19], v[24:25]
	v_pk_add_f32 v[10:11], v[36:37], v[38:39] neg_lo:[0,1] neg_hi:[0,1]
	v_pk_fma_f32 v[8:9], v[8:9], v[20:21], v[14:15] neg_lo:[0,0,1] neg_hi:[0,0,1]
	v_pk_add_f32 v[14:15], v[28:29], v[30:31] neg_lo:[0,1] neg_hi:[0,1]
	v_mov_b32_e32 v23, v2
	v_mov_b32_e32 v33, v3
	v_pk_fma_f32 v[0:1], v[0:1], v[20:21], v[26:27]
	v_pk_add_f32 v[2:3], v[22:23], v[32:33]
	v_mov_b32_e32 v21, v11
	v_mov_b32_e32 v20, v10
	v_mov_b32_e32 v19, v15
	v_mov_b32_e32 v18, v14
	s_branch .LBB0_360
